# speedup vs baseline: 1.0105x; 1.0047x over previous
; DEV unsigned cvtpk(float lo, float hi) { f32x2_t v = {lo, hi}; bf16x2_t b = __builtin_convertvector(v, bf16x2_t); return __builtin_bit_cast(unsigned, b); }
; DEV float wave_sum(float v) { for (int o = 32; o >= 1; o >>= 1) v += __shfl_xor(v, o); return v; }
; DEV void init_rows(const Params& p) {
;     ...
;   for (int row = blockIdx.x * 8 + wid; row < SEQ; row += gridDim.x * 8) {
;     const float* xr = p.x + (size_t)row * DM; float ss = 0;
; #pragma unroll
;     for (int c = 0; c < 4; ++c) { const int idx = c * 512 + lane * 8;
;       const f32x4 v = *reinterpret_cast<const f32x4*>(xr + idx), u = *reinterpret_cast<const f32x4*>(xr + idx + 4);
;       const u32x4 w = {cvtpk(v[0], v[1]), cvtpk(v[2], v[3]), cvtpk(u[0], u[1]), cvtpk(u[2], u[3])};
;       *reinterpret_cast<u32x4*>(xb + (size_t)row * DM + idx) = w;
; #pragma unroll
;       for (int e = 0; e < 4; ++e) { const float lo = __uint_as_float(w[e] << 16), hi = __uint_as_float(w[e] & 0xffff0000u); ss += lo * lo + hi * hi; } }
;     ss = wave_sum(ss);
;     if (lane == 0) rstd[row] = rsqrtf(ss * (1.f / DM) + EPS);
;   }
.LBB0_58:
	v_ashrrev_i32_e32 v1, 31, v0
	v_readlane_b32 s12, v252, 0
	s_waitcnt vmcnt(2) lgkmcnt(0)
	v_lshlrev_b64 v[18:19], 13, v[0:1]
	v_readlane_b32 s13, v252, 1
	v_lshlrev_b64 v[28:29], 12, v[0:1]
	v_lshl_add_u64 v[38:39], v[4:5], 0, v[28:29]
	v_lshl_add_u64 v[34:35], s[12:13], 0, v[18:19]
	v_lshl_add_u64 v[26:27], v[34:35], 0, v[2:3]
	global_load_dwordx4 v[18:21], v[26:27], off nt
	global_load_dwordx4 v[22:25], v[26:27], off offset:16 nt
	v_lshl_add_u64 v[30:31], v[34:35], 0, v[6:7]
	v_lshl_add_u64 v[34:35], v[34:35], 0, v[8:9]
	v_readlane_b32 s14, v252, 2
	v_readlane_b32 s15, v252, 3
	v_readlane_b32 s16, v252, 4
	v_readlane_b32 s17, v252, 5
	v_readlane_b32 s18, v252, 6
	v_readlane_b32 s19, v252, 7
	v_readlane_b32 s20, v252, 8
	v_readlane_b32 s21, v252, 9
	v_readlane_b32 s22, v252, 10
	v_readlane_b32 s23, v252, 11
	v_readlane_b32 s24, v252, 12
	v_readlane_b32 s25, v252, 13
	v_readlane_b32 s26, v252, 14
	v_readlane_b32 s27, v252, 15
	s_waitcnt vmcnt(1)
	v_cvt_pk_bf16_f32 v18, v18, v19
	v_cvt_pk_bf16_f32 v19, v20, v21
	s_waitcnt vmcnt(0)
	v_cvt_pk_bf16_f32 v20, v22, v23
	v_cvt_pk_bf16_f32 v21, v24, v25
	global_store_dwordx4 v[38:39], v[18:21], off
	global_load_dwordx4 v[22:25], v[26:27], off offset:2048 nt
	s_nop 0
	global_load_dwordx4 v[26:29], v[26:27], off offset:2064 nt
	v_lshlrev_b32_e32 v40, 16, v18
	v_and_b32_e32 v18, 0xffff0000, v18
	v_lshlrev_b32_e32 v41, 16, v19
	v_and_b32_e32 v19, 0xffff0000, v19
	v_lshlrev_b32_e32 v42, 16, v20
	v_and_b32_e32 v20, 0xffff0000, v20
	v_mul_f32_e32 v18, v18, v18
	v_mul_f32_e32 v19, v19, v19
	v_mul_f32_e32 v20, v20, v20
	v_fmac_f32_e32 v18, v40, v40
	v_fmac_f32_e32 v19, v41, v41
	v_lshlrev_b32_e32 v43, 16, v21
	v_and_b32_e32 v21, 0xffff0000, v21
	v_fmac_f32_e32 v20, v42, v42
	v_add_f32_e32 v18, v18, v19
	v_mul_f32_e32 v21, v21, v21
	v_add_f32_e32 v18, v18, v20
	v_fmac_f32_e32 v21, v43, v43
	v_add_f32_e32 v18, v21, v18
	s_waitcnt vmcnt(1)
	v_cvt_pk_bf16_f32 v22, v22, v23
	v_cvt_pk_bf16_f32 v23, v24, v25
	s_waitcnt vmcnt(0)
	v_cvt_pk_bf16_f32 v24, v26, v27
	v_cvt_pk_bf16_f32 v25, v28, v29
	global_store_dwordx4 v[38:39], v[22:25], off offset:1024
	global_load_dwordx4 v[26:29], v[30:31], off nt
	s_nop 0
	global_load_dwordx4 v[30:33], v[30:31], off offset:16 nt
	v_and_b32_e32 v20, 0xffff0000, v22
	v_lshlrev_b32_e32 v19, 16, v22
	v_and_b32_e32 v22, 0xffff0000, v23
	v_mul_f32_e32 v20, v20, v20
	v_lshlrev_b32_e32 v21, 16, v23
	v_lshlrev_b32_e32 v23, 16, v24
	v_and_b32_e32 v24, 0xffff0000, v24
	v_mul_f32_e32 v22, v22, v22
	v_fmac_f32_e32 v20, v19, v19
	v_lshlrev_b32_e32 v40, 16, v25
	v_and_b32_e32 v25, 0xffff0000, v25
	v_mul_f32_e32 v24, v24, v24
	v_fmac_f32_e32 v22, v21, v21
	v_add_f32_e32 v18, v18, v20
	v_mul_f32_e32 v25, v25, v25
	v_fmac_f32_e32 v24, v23, v23
	v_add_f32_e32 v18, v22, v18
	v_fmac_f32_e32 v25, v40, v40
	v_add_f32_e32 v18, v24, v18
	v_add_f32_e32 v18, v25, v18
	s_waitcnt vmcnt(1)
	v_cvt_pk_bf16_f32 v26, v26, v27
	v_cvt_pk_bf16_f32 v27, v28, v29
	s_waitcnt vmcnt(0)
	v_cvt_pk_bf16_f32 v28, v30, v31
	v_cvt_pk_bf16_f32 v29, v32, v33
	global_store_dwordx4 v[38:39], v[26:29], off offset:2048
	global_load_dwordx4 v[30:33], v[34:35], off nt
	s_nop 0
	global_load_dwordx4 v[34:37], v[34:35], off offset:16 nt
	v_and_b32_e32 v20, 0xffff0000, v26
	v_lshlrev_b32_e32 v19, 16, v26
	v_and_b32_e32 v22, 0xffff0000, v27
	v_mul_f32_e32 v20, v20, v20
	v_lshlrev_b32_e32 v21, 16, v27
	v_and_b32_e32 v24, 0xffff0000, v28
	v_mul_f32_e32 v22, v22, v22
	v_fmac_f32_e32 v20, v19, v19
	v_lshlrev_b32_e32 v23, 16, v28
	v_and_b32_e32 v26, 0xffff0000, v29
	v_mul_f32_e32 v24, v24, v24
	v_fmac_f32_e32 v22, v21, v21
	v_add_f32_e32 v18, v20, v18
	v_lshlrev_b32_e32 v25, 16, v29
	v_mul_f32_e32 v26, v26, v26
	v_fmac_f32_e32 v24, v23, v23
	v_add_f32_e32 v18, v22, v18
	v_fmac_f32_e32 v26, v25, v25
	v_add_f32_e32 v18, v24, v18
	v_add_f32_e32 v18, v26, v18
	s_waitcnt vmcnt(1)
	v_cvt_pk_bf16_f32 v20, v30, v31
	v_cvt_pk_bf16_f32 v21, v32, v33
	v_and_b32_e32 v24, 0xffff0000, v20
	s_waitcnt vmcnt(0)
	v_cvt_pk_bf16_f32 v22, v34, v35
	v_lshlrev_b32_e32 v19, 16, v20
	v_and_b32_e32 v26, 0xffff0000, v21
	v_mul_f32_e32 v24, v24, v24
	v_cvt_pk_bf16_f32 v23, v36, v37
	v_lshlrev_b32_e32 v25, 16, v21
	v_and_b32_e32 v28, 0xffff0000, v22
	v_mul_f32_e32 v26, v26, v26
	v_fmac_f32_e32 v24, v19, v19
	v_lshlrev_b32_e32 v27, 16, v22
	v_and_b32_e32 v30, 0xffff0000, v23
	v_mul_f32_e32 v28, v28, v28
	v_fmac_f32_e32 v26, v25, v25
	v_add_f32_e32 v18, v24, v18
	v_lshlrev_b32_e32 v29, 16, v23
	v_mul_f32_e32 v30, v30, v30
	v_fmac_f32_e32 v28, v27, v27
	v_add_f32_e32 v18, v26, v18
	v_add_f32_e32 v18, v28, v18
	v_fmac_f32_e32 v30, v29, v29
	v_add_f32_e32 v18, v30, v18
	ds_bpermute_b32 v19, v11, v18
	global_store_dwordx4 v[38:39], v[20:23], off offset:3072
	s_waitcnt lgkmcnt(0)
	v_add_f32_e32 v18, v18, v19
	ds_bpermute_b32 v19, v12, v18
	s_waitcnt lgkmcnt(0)
	v_add_f32_e32 v18, v18, v19
	ds_bpermute_b32 v19, v13, v18
	s_waitcnt lgkmcnt(0)
	v_add_f32_e32 v18, v18, v19
	ds_bpermute_b32 v19, v14, v18
	s_waitcnt lgkmcnt(0)
	v_add_f32_e32 v18, v18, v19
	ds_bpermute_b32 v19, v15, v18
	s_waitcnt lgkmcnt(0)
	v_add_f32_e32 v18, v18, v19
	ds_bpermute_b32 v19, v16, v18
	s_and_saveexec_b64 s[6:7], vcc
	s_cbranch_execz .LBB0_57
	s_waitcnt lgkmcnt(0)
	v_add_f32_e32 v18, v18, v19
	v_fmamk_f32 v18, v18, 0x3a000000, v17
	v_mul_f32_e32 v19, 0x4b800000, v18
	v_cmp_gt_f32_e64 s[0:1], s9, v18
	s_nop 1
	v_cndmask_b32_e64 v18, v18, v19, s[0:1]
	v_rsq_f32_e32 v18, v18
	s_nop 0
	v_mul_f32_e32 v19, 0x45800000, v18
	v_cndmask_b32_e64 v20, v18, v19, s[0:1]
	v_lshl_add_u64 v[18:19], v[0:1], 2, s[68:69]
	global_store_dword v[18:19], v20, off
	s_branch .LBB0_57

; DEV float wave_sum(float v) { for (int o = 32; o >= 1; o >>= 1) v += __shfl_xor(v, o); return v; }
; DEV void post_rows(const Params& p, const float* __restrict__ xsrc, const float* __restrict__ g, bool final) {
;     ...
;   for (int row = blockIdx.x * 8 + wid; row < SEQ; row += gridDim.x * 8) {
;     float mv[32]; float ss = 0;
; #pragma unroll
;     for (int c = 0; c < 4; ++c) { const int idx = c * 512 + lane * 8; const u32x4 w = *reinterpret_cast<const u32x4*>(mb + (size_t)row * DM + idx);
; #pragma unroll
;       for (int e = 0; e < 4; ++e) { const float lo = __uint_as_float(w[e] << 16), hi = __uint_as_float(w[e] & 0xffff0000u);
;         mv[c * 8 + 2 * e] = lo; mv[c * 8 + 2 * e + 1] = hi; ss += lo * lo + hi * hi; } }
;     ss = wave_sum(ss);
;     const float rm = rsqrtf(ss * (1.f / DM) + EPS);
;     float sx = 0;
; #pragma unroll
;     for (int c = 0; c < 4; ++c) { const int idx = c * 512 + lane * 8;
;       float xo[8];
;       if (xsrc) { const f32x4 a = *reinterpret_cast<const f32x4*>(xsrc + (size_t)row * DM + idx), b = *reinterpret_cast<const f32x4*>(xsrc + (size_t)row * DM + idx + 4);
; #pragma unroll
;         for (int e = 0; e < 4; ++e) { xo[e] = a[e]; xo[4 + e] = b[e]; } }
;       else { const u32x4 w = *reinterpret_cast<const u32x4*>(xb + (size_t)row * DM + idx);
; #pragma unroll
;         for (int e = 0; e < 4; ++e) { xo[2 * e] = __uint_as_float(w[e] << 16); xo[2 * e + 1] = __uint_as_float(w[e] & 0xffff0000u); } }
.LBB0_555:
	v_ashrrev_i32_e32 v33, 31, v32
	v_lshlrev_b64 v[38:39], 12, v[32:33]
	v_lshl_add_u64 v[56:57], v[34:35], 0, v[38:39]
	s_waitcnt lgkmcnt(0)
	global_load_dwordx4 v[40:43], v[56:57], off nt
	v_lshl_add_u64 v[38:39], v[36:37], 0, v[38:39]
	global_load_dwordx4 v[44:47], v[38:39], off nt
	global_load_dwordx4 v[48:51], v[56:57], off offset:1024 nt
	global_load_dwordx4 v[52:55], v[56:57], off offset:2048 nt
	s_nop 0
	global_load_dwordx4 v[56:59], v[56:57], off offset:3072 nt
	s_nop 0
	global_load_dwordx4 v[60:63], v[38:39], off offset:1024 nt
	global_load_dwordx4 v[64:67], v[38:39], off offset:2048 nt
	global_load_dwordx4 v[68:71], v[38:39], off offset:3072 nt
	s_waitcnt vmcnt(6)
	v_lshlrev_b32_e32 v74, 16, v47
	v_and_b32_e32 v75, 0xffff0000, v47
	v_lshlrev_b32_e32 v78, 16, v46
	v_and_b32_e32 v79, 0xffff0000, v46
	v_lshlrev_b32_e32 v46, 16, v41
	v_and_b32_e32 v47, 0xffff0000, v41
	v_lshlrev_b32_e32 v82, 16, v40
	v_and_b32_e32 v83, 0xffff0000, v40
	v_lshlrev_b32_e32 v72, 16, v43
	v_and_b32_e32 v73, 0xffff0000, v43
	v_lshlrev_b32_e32 v76, 16, v42
	v_and_b32_e32 v77, 0xffff0000, v42
	s_waitcnt vmcnt(3)
	v_lshlrev_b32_e32 v40, 16, v59
	v_and_b32_e32 v41, 0xffff0000, v59
	v_lshlrev_b32_e32 v42, 16, v58
	v_and_b32_e32 v43, 0xffff0000, v58
	v_lshlrev_b32_e32 v58, 16, v57
	v_and_b32_e32 v59, 0xffff0000, v57
	v_lshlrev_b32_e32 v96, 16, v56
	v_and_b32_e32 v97, 0xffff0000, v56
	v_pk_mul_f32 v[56:57], v[46:47], v[46:47]
	v_pk_mul_f32 v[98:99], v[82:83], v[82:83]
	v_lshlrev_b32_e32 v90, 16, v55
	v_and_b32_e32 v91, 0xffff0000, v55
	v_lshlrev_b32_e32 v92, 16, v54
	v_and_b32_e32 v93, 0xffff0000, v54
	v_lshlrev_b32_e32 v54, 16, v53
	v_and_b32_e32 v55, 0xffff0000, v53
	v_lshlrev_b32_e32 v94, 16, v52
	v_and_b32_e32 v95, 0xffff0000, v52
	v_pk_mul_f32 v[52:53], v[76:77], v[76:77]
	v_add_f32_e32 v56, v56, v57
	v_add_f32_e32 v57, v98, v99
	v_lshlrev_b32_e32 v84, 16, v51
	v_and_b32_e32 v85, 0xffff0000, v51
	v_lshlrev_b32_e32 v86, 16, v50
	v_and_b32_e32 v87, 0xffff0000, v50
	v_lshlrev_b32_e32 v50, 16, v49
	v_and_b32_e32 v51, 0xffff0000, v49
	v_lshlrev_b32_e32 v88, 16, v48
	v_and_b32_e32 v89, 0xffff0000, v48
	v_pk_mul_f32 v[48:49], v[72:73], v[72:73]
	v_add_f32_e32 v81, v52, v53
	v_add_f32_e32 v56, v57, v56
	v_pk_mul_f32 v[106:107], v[88:89], v[88:89]
	v_add_f32_e32 v98, v48, v49
	v_add_f32_e32 v56, v81, v56
	v_pk_mul_f32 v[104:105], v[50:51], v[50:51]
	v_add_f32_e32 v99, v106, v107
	v_add_f32_e32 v56, v98, v56
	v_pk_mul_f32 v[102:103], v[86:87], v[86:87]
	v_add_f32_e32 v104, v104, v105
	v_add_f32_e32 v56, v99, v56
	v_pk_mul_f32 v[100:101], v[84:85], v[84:85]
	v_add_f32_e32 v102, v102, v103
	v_add_f32_e32 v56, v104, v56
	v_pk_mul_f32 v[114:115], v[94:95], v[94:95]
	v_add_f32_e32 v100, v100, v101
	v_add_f32_e32 v56, v102, v56
	v_pk_mul_f32 v[112:113], v[54:55], v[54:55]
	v_add_f32_e32 v101, v114, v115
	v_add_f32_e32 v56, v100, v56
	v_pk_mul_f32 v[110:111], v[92:93], v[92:93]
	v_add_f32_e32 v103, v112, v113
	v_add_f32_e32 v56, v101, v56
	v_pk_mul_f32 v[108:109], v[90:91], v[90:91]
	v_mov_b32_e32 v122, v59
	v_mov_b32_e32 v123, v97
	v_add_f32_e32 v105, v110, v111
	v_add_f32_e32 v56, v103, v56
	v_mov_b32_e32 v120, v58
	v_mov_b32_e32 v121, v96
	v_pk_mul_f32 v[122:123], v[122:123], v[122:123]
	v_add_f32_e32 v106, v108, v109
	v_add_f32_e32 v56, v105, v56
	v_mov_b32_e32 v118, v41
	v_mov_b32_e32 v119, v43
	v_pk_fma_f32 v[52:53], v[120:121], v[120:121], v[122:123]
	v_add_f32_e32 v56, v106, v56
	v_mov_b32_e32 v116, v40
	v_mov_b32_e32 v117, v42
	v_pk_mul_f32 v[118:119], v[118:119], v[118:119]
	v_add_f32_e32 v53, v53, v56
	v_pk_fma_f32 v[48:49], v[116:117], v[116:117], v[118:119]
	v_add_f32_e32 v52, v52, v53
	v_add_f32_e32 v49, v49, v52
	v_add_f32_e32 v53, v48, v49
	ds_bpermute_b32 v56, v216, v53
	v_lshlrev_b32_e32 v48, 16, v44
	v_and_b32_e32 v49, 0xffff0000, v44
	v_lshlrev_b32_e32 v80, 16, v45
	v_and_b32_e32 v81, 0xffff0000, v45
	s_waitcnt lgkmcnt(0)
	v_add_f32_e32 v44, v53, v56
	ds_bpermute_b32 v45, v217, v44
	s_waitcnt vmcnt(0)
	v_lshlrev_b32_e32 v106, 16, v68
	v_and_b32_e32 v107, 0xffff0000, v68
	v_lshlrev_b32_e32 v52, 16, v63
	v_and_b32_e32 v53, 0xffff0000, v63
	s_waitcnt lgkmcnt(0)
	v_add_f32_e32 v44, v44, v45
	ds_bpermute_b32 v45, v218, v44
	v_lshlrev_b32_e32 v56, 16, v62
	v_and_b32_e32 v57, 0xffff0000, v62
	v_lshlrev_b32_e32 v62, 16, v61
	v_and_b32_e32 v63, 0xffff0000, v61
	s_waitcnt lgkmcnt(0)
	v_add_f32_e32 v44, v44, v45
	ds_bpermute_b32 v45, v219, v44
	v_lshlrev_b32_e32 v98, 16, v60
	v_and_b32_e32 v99, 0xffff0000, v60
	v_lshlrev_b32_e32 v60, 16, v67
	v_and_b32_e32 v61, 0xffff0000, v67
	s_waitcnt lgkmcnt(0)
	v_add_f32_e32 v44, v44, v45
	ds_bpermute_b32 v45, v220, v44
	v_lshlrev_b32_e32 v100, 16, v66
	v_and_b32_e32 v101, 0xffff0000, v66
	v_lshlrev_b32_e32 v66, 16, v65
	v_and_b32_e32 v67, 0xffff0000, v65
	s_waitcnt lgkmcnt(0)
	v_add_f32_e32 v44, v44, v45
	ds_bpermute_b32 v45, v221, v44
	v_lshlrev_b32_e32 v102, 16, v64
	v_and_b32_e32 v103, 0xffff0000, v64
	v_lshlrev_b32_e32 v64, 16, v71
	v_and_b32_e32 v65, 0xffff0000, v71
	s_waitcnt lgkmcnt(0)
; DEV unsigned cvtpk(float lo, float hi) { f32x2_t v = {lo, hi}; bf16x2_t b = __builtin_convertvector(v, bf16x2_t); return __builtin_bit_cast(unsigned, b); }
; DEV float wave_sum(float v) { for (int o = 32; o >= 1; o >>= 1) v += __shfl_xor(v, o); return v; }
; DEV void post_rows(const Params& p, const float* __restrict__ xsrc, const float* __restrict__ g, bool final) {
;     ...
;     ss = wave_sum(ss);
;     const float rm = rsqrtf(ss * (1.f / DM) + EPS);
;     float sx = 0;
; #pragma unroll
;     for (int c = 0; c < 4; ++c) { const int idx = c * 512 + lane * 8;
;       float xo[8];
;       if (xsrc) { const f32x4 a = *reinterpret_cast<const f32x4*>(xsrc + (size_t)row * DM + idx), b = *reinterpret_cast<const f32x4*>(xsrc + (size_t)row * DM + idx + 4);
; #pragma unroll
;         for (int e = 0; e < 4; ++e) { xo[e] = a[e]; xo[4 + e] = b[e]; } }
;       else { const u32x4 w = *reinterpret_cast<const u32x4*>(xb + (size_t)row * DM + idx);
; #pragma unroll
;         for (int e = 0; e < 4; ++e) { xo[2 * e] = __uint_as_float(w[e] << 16); xo[2 * e + 1] = __uint_as_float(w[e] & 0xffff0000u); } }
;       const f32x4 g0 = *reinterpret_cast<const f32x4*>(g + idx), g1 = *reinterpret_cast<const f32x4*>(g + idx + 4);
;       float xn[8];
; #pragma unroll
;       for (int e = 0; e < 4; ++e) { xn[e] = xo[e] + mv[c * 8 + e] * rm * g0[e]; xn[4 + e] = xo[4 + e] + mv[c * 8 + 4 + e] * rm * g1[e]; }
;       if (final) { *reinterpret_cast<f32x4*>(p.out + (size_t)row * DM + idx) = (f32x4){xn[0], xn[1], xn[2], xn[3]};
;                    *reinterpret_cast<f32x4*>(p.out + (size_t)row * DM + idx + 4) = (f32x4){xn[4], xn[5], xn[6], xn[7]}; }
;       else { const u32x4 w = {cvtpk(xn[0], xn[1]), cvtpk(xn[2], xn[3]), cvtpk(xn[4], xn[5]), cvtpk(xn[6], xn[7])};
;         *reinterpret_cast<u32x4*>(xb + (size_t)row * DM + idx) = w;
; #pragma unroll
;         for (int e = 0; e < 4; ++e) { const float lo = __uint_as_float(w[e] << 16), hi = __uint_as_float(w[e] & 0xffff0000u); sx += lo * lo + hi * hi; } } }
;     if (!final) { sx = wave_sum(sx); if (lane == 0) rstd[row] = rsqrtf(sx * (1.f / DM) + EPS); }
	v_add_f32_e32 v44, v44, v45
	v_mov_b32_e32 v45, 0x358637bd
	v_fmamk_f32 v44, v44, 0x3a000000, v45
	v_mul_f32_e32 v45, 0x4b800000, v44
	v_cmp_gt_f32_e64 s[0:1], s33, v44
	v_lshlrev_b32_e32 v104, 16, v70
	v_and_b32_e32 v105, 0xffff0000, v70
	v_cndmask_b32_e64 v44, v44, v45, s[0:1]
	v_rsq_f32_e32 v44, v44
	v_lshlrev_b32_e32 v70, 16, v69
	v_and_b32_e32 v71, 0xffff0000, v69
	v_mul_f32_e32 v45, 0x45800000, v44
	v_cndmask_b32_e64 v68, v44, v45, s[0:1]
	v_pk_mul_f32 v[44:45], v[68:69], v[82:83] op_sel_hi:[0,1]
	v_pk_fma_f32 v[44:45], v[0:1], v[44:45], v[48:49]
	v_pk_mul_f32 v[48:49], v[68:69], v[76:77] op_sel_hi:[0,1]
	v_pk_mul_f32 v[46:47], v[68:69], v[46:47] op_sel_hi:[0,1]
	v_pk_fma_f32 v[48:49], v[4:5], v[48:49], v[78:79]
	v_pk_fma_f32 v[46:47], v[2:3], v[46:47], v[80:81]
	v_cvt_pk_bf16_f32 v44, v44, v45
	v_cvt_pk_bf16_f32 v45, v46, v47
	v_cvt_pk_bf16_f32 v46, v48, v49
	v_and_b32_e32 v49, 0xffff0000, v44
	v_pk_mul_f32 v[72:73], v[68:69], v[72:73] op_sel_hi:[0,1]
	v_lshlrev_b32_e32 v48, 16, v44
	v_mul_f32_e32 v49, v49, v49
	v_and_b32_e32 v69, 0xffff0000, v45
	v_fmac_f32_e32 v49, v48, v48
	v_lshlrev_b32_e32 v48, 16, v45
	v_mul_f32_e32 v69, v69, v69
	v_fmac_f32_e32 v69, v48, v48
	v_add_f32_e32 v48, v49, v69
	v_and_b32_e32 v69, 0xffff0000, v46
	v_pk_fma_f32 v[72:73], v[6:7], v[72:73], v[74:75]
	v_lshlrev_b32_e32 v49, 16, v46
	v_mul_f32_e32 v69, v69, v69
	v_cvt_pk_bf16_f32 v47, v72, v73
	v_fmac_f32_e32 v69, v49, v49
	v_add_f32_e32 v48, v69, v48
	v_and_b32_e32 v69, 0xffff0000, v47
	v_lshlrev_b32_e32 v49, 16, v47
	v_mul_f32_e32 v69, v69, v69
	v_fmac_f32_e32 v69, v49, v49
	v_add_f32_e32 v69, v69, v48
	v_pk_mul_f32 v[48:49], v[68:69], v[88:89] op_sel_hi:[0,1]
	v_pk_mul_f32 v[50:51], v[68:69], v[50:51] op_sel_hi:[0,1]
	v_pk_fma_f32 v[48:49], v[8:9], v[48:49], v[98:99]
	v_pk_fma_f32 v[50:51], v[10:11], v[50:51], v[62:63]
	v_pk_mul_f32 v[62:63], v[68:69], v[84:85] op_sel_hi:[0,1]
	v_pk_fma_f32 v[52:53], v[14:15], v[62:63], v[52:53]
	v_cvt_pk_bf16_f32 v48, v48, v49
	v_pk_mul_f32 v[72:73], v[68:69], v[86:87] op_sel_hi:[0,1]
	v_cvt_pk_bf16_f32 v49, v50, v51
	v_cvt_pk_bf16_f32 v51, v52, v53
	v_and_b32_e32 v53, 0xffff0000, v48
	v_pk_fma_f32 v[56:57], v[12:13], v[72:73], v[56:57]
	v_lshlrev_b32_e32 v52, 16, v48
	v_mul_f32_e32 v53, v53, v53
	v_cvt_pk_bf16_f32 v50, v56, v57
	v_fmac_f32_e32 v53, v52, v52
	v_and_b32_e32 v56, 0xffff0000, v49
	v_add_f32_e32 v52, v53, v69
	v_lshlrev_b32_e32 v53, 16, v49
	v_mul_f32_e32 v56, v56, v56
	v_fmac_f32_e32 v56, v53, v53
	v_add_f32_e32 v52, v56, v52
	v_and_b32_e32 v56, 0xffff0000, v50
	v_lshlrev_b32_e32 v53, 16, v50
	v_mul_f32_e32 v56, v56, v56
	v_fmac_f32_e32 v56, v53, v53
	v_add_f32_e32 v52, v56, v52
	v_and_b32_e32 v56, 0xffff0000, v51
	v_lshlrev_b32_e32 v53, 16, v51
	v_mul_f32_e32 v56, v56, v56
	v_fmac_f32_e32 v56, v53, v53
	v_add_f32_e32 v69, v56, v52
	v_pk_mul_f32 v[52:53], v[68:69], v[94:95] op_sel_hi:[0,1]
	v_pk_fma_f32 v[52:53], v[16:17], v[52:53], v[102:103]
	v_pk_mul_f32 v[56:57], v[68:69], v[92:93] op_sel_hi:[0,1]
	v_pk_mul_f32 v[54:55], v[68:69], v[54:55] op_sel_hi:[0,1]
	v_pk_fma_f32 v[56:57], v[20:21], v[56:57], v[100:101]
	v_pk_fma_f32 v[54:55], v[18:19], v[54:55], v[66:67]
	v_cvt_pk_bf16_f32 v52, v52, v53
	v_pk_mul_f32 v[62:63], v[68:69], v[90:91] op_sel_hi:[0,1]
	v_cvt_pk_bf16_f32 v53, v54, v55
	v_cvt_pk_bf16_f32 v54, v56, v57
	v_and_b32_e32 v57, 0xffff0000, v52
	v_pk_fma_f32 v[60:61], v[22:23], v[62:63], v[60:61]
	v_lshlrev_b32_e32 v56, 16, v52
	v_mul_f32_e32 v57, v57, v57
	v_cvt_pk_bf16_f32 v55, v60, v61
	v_fmac_f32_e32 v57, v56, v56
	v_and_b32_e32 v60, 0xffff0000, v53
	v_add_f32_e32 v56, v57, v69
	v_lshlrev_b32_e32 v57, 16, v53
	v_mul_f32_e32 v60, v60, v60
	v_fmac_f32_e32 v60, v57, v57
	v_add_f32_e32 v56, v60, v56
	v_and_b32_e32 v60, 0xffff0000, v54
	v_lshlrev_b32_e32 v57, 16, v54
	v_mul_f32_e32 v60, v60, v60
	v_fmac_f32_e32 v60, v57, v57
	v_add_f32_e32 v56, v60, v56
	v_and_b32_e32 v60, 0xffff0000, v55
	v_lshlrev_b32_e32 v57, 16, v55
	v_mul_f32_e32 v60, v60, v60
	v_fmac_f32_e32 v60, v57, v57
	v_add_f32_e32 v60, v60, v56
	v_pk_mul_f32 v[56:57], v[68:69], v[96:97] op_sel_hi:[0,1]
	v_pk_fma_f32 v[56:57], v[24:25], v[56:57], v[106:107]
	v_pk_mul_f32 v[58:59], v[68:69], v[58:59] op_sel_hi:[0,1]
	v_pk_mul_f32 v[40:41], v[68:69], v[40:41] op_sel_hi:[0,1]
	v_pk_fma_f32 v[58:59], v[26:27], v[58:59], v[70:71]
	v_pk_fma_f32 v[40:41], v[30:31], v[40:41], v[64:65]
	v_cvt_pk_bf16_f32 v56, v56, v57
	v_pk_mul_f32 v[42:43], v[68:69], v[42:43] op_sel_hi:[0,1]
	v_cvt_pk_bf16_f32 v57, v58, v59
	v_cvt_pk_bf16_f32 v59, v40, v41
	v_and_b32_e32 v41, 0xffff0000, v56
	v_pk_fma_f32 v[42:43], v[28:29], v[42:43], v[104:105]
	v_lshlrev_b32_e32 v40, 16, v56
	v_mul_f32_e32 v41, v41, v41
	v_cvt_pk_bf16_f32 v58, v42, v43
	v_fmac_f32_e32 v41, v40, v40
	v_and_b32_e32 v42, 0xffff0000, v57
	v_add_f32_e32 v40, v41, v60
	v_lshlrev_b32_e32 v41, 16, v57
	v_mul_f32_e32 v42, v42, v42
	v_fmac_f32_e32 v42, v41, v41
	v_add_f32_e32 v40, v42, v40
	v_and_b32_e32 v42, 0xffff0000, v58
	v_lshlrev_b32_e32 v41, 16, v58
	v_mul_f32_e32 v42, v42, v42
	v_fmac_f32_e32 v42, v41, v41
	v_add_f32_e32 v40, v42, v40
	v_and_b32_e32 v42, 0xffff0000, v59
	v_lshlrev_b32_e32 v41, 16, v59
	v_mul_f32_e32 v42, v42, v42
	v_fmac_f32_e32 v42, v41, v41
	v_add_f32_e32 v40, v42, v40
	ds_bpermute_b32 v41, v216, v40
	global_store_dwordx4 v[38:39], v[44:47], off
	global_store_dwordx4 v[38:39], v[48:51], off offset:1024
	global_store_dwordx4 v[38:39], v[52:55], off offset:2048
	global_store_dwordx4 v[38:39], v[56:59], off offset:3072
	s_waitcnt lgkmcnt(0)
	v_add_f32_e32 v40, v40, v41
	ds_bpermute_b32 v41, v217, v40
	s_waitcnt lgkmcnt(0)
	v_add_f32_e32 v40, v40, v41
	ds_bpermute_b32 v41, v218, v40
	s_waitcnt lgkmcnt(0)
	v_add_f32_e32 v40, v40, v41
	ds_bpermute_b32 v41, v219, v40
	s_waitcnt lgkmcnt(0)
	v_add_f32_e32 v40, v40, v41
	ds_bpermute_b32 v41, v220, v40
	s_waitcnt lgkmcnt(0)
	v_add_f32_e32 v40, v40, v41
	ds_bpermute_b32 v41, v221, v40
	s_and_saveexec_b64 s[10:11], vcc
	s_cbranch_execz .LBB0_554
	s_waitcnt lgkmcnt(0)
	v_add_f32_e32 v38, v40, v41
	v_mov_b32_e32 v39, 0x358637bd
	v_fmamk_f32 v38, v38, 0x3a000000, v39
	v_mul_f32_e32 v39, 0x4b800000, v38
	v_cmp_gt_f32_e64 s[0:1], s33, v38
	s_nop 1
	v_cndmask_b32_e64 v38, v38, v39, s[0:1]
	v_rsq_f32_e32 v38, v38
	s_nop 0
	v_mul_f32_e32 v39, 0x45800000, v38
	v_cndmask_b32_e64 v40, v38, v39, s[0:1]
	v_lshl_add_u64 v[38:39], v[32:33], 2, s[68:69]
	global_store_dword v[38:39], v40, off
	s_branch .LBB0_554

; DEV unsigned cvtpk(float lo, float hi) { f32x2_t v = {lo, hi}; bf16x2_t b = __builtin_convertvector(v, bf16x2_t); return __builtin_bit_cast(unsigned, b); }
; DEV float wave_sum(float v) { for (int o = 32; o >= 1; o >>= 1) v += __shfl_xor(v, o); return v; }
; DEV void post_rows(const Params& p, const float* __restrict__ xsrc, const float* __restrict__ g, bool final) {
;     ...
;   for (int row = blockIdx.x * 8 + wid; row < SEQ; row += gridDim.x * 8) {
;     float mv[32]; float ss = 0;
; #pragma unroll
;     for (int c = 0; c < 4; ++c) { const int idx = c * 512 + lane * 8; const u32x4 w = *reinterpret_cast<const u32x4*>(mb + (size_t)row * DM + idx);
; #pragma unroll
;       for (int e = 0; e < 4; ++e) { const float lo = __uint_as_float(w[e] << 16), hi = __uint_as_float(w[e] & 0xffff0000u);
;         mv[c * 8 + 2 * e] = lo; mv[c * 8 + 2 * e + 1] = hi; ss += lo * lo + hi * hi; } }
;     ss = wave_sum(ss);
;     const float rm = rsqrtf(ss * (1.f / DM) + EPS);
;     float sx = 0;
; #pragma unroll
;     for (int c = 0; c < 4; ++c) { const int idx = c * 512 + lane * 8;
;       float xo[8];
;       if (xsrc) { const f32x4 a = *reinterpret_cast<const f32x4*>(xsrc + (size_t)row * DM + idx), b = *reinterpret_cast<const f32x4*>(xsrc + (size_t)row * DM + idx + 4);
; #pragma unroll
;         for (int e = 0; e < 4; ++e) { xo[e] = a[e]; xo[4 + e] = b[e]; } }
;       else { const u32x4 w = *reinterpret_cast<const u32x4*>(xb + (size_t)row * DM + idx);
; #pragma unroll
;         for (int e = 0; e < 4; ++e) { xo[2 * e] = __uint_as_float(w[e] << 16); xo[2 * e + 1] = __uint_as_float(w[e] & 0xffff0000u); } }
;       const f32x4 g0 = *reinterpret_cast<const f32x4*>(g + idx), g1 = *reinterpret_cast<const f32x4*>(g + idx + 4);
;       float xn[8];
; #pragma unroll
;       for (int e = 0; e < 4; ++e) { xn[e] = xo[e] + mv[c * 8 + e] * rm * g0[e]; xn[4 + e] = xo[4 + e] + mv[c * 8 + 4 + e] * rm * g1[e]; }
;       if (final) { *reinterpret_cast<f32x4*>(p.out + (size_t)row * DM + idx) = (f32x4){xn[0], xn[1], xn[2], xn[3]};
;                    *reinterpret_cast<f32x4*>(p.out + (size_t)row * DM + idx + 4) = (f32x4){xn[4], xn[5], xn[6], xn[7]}; }
;       else { const u32x4 w = {cvtpk(xn[0], xn[1]), cvtpk(xn[2], xn[3]), cvtpk(xn[4], xn[5]), cvtpk(xn[6], xn[7])};
.LBB0_753:
	v_ashrrev_i32_e32 v41, 31, v40
	v_lshlrev_b64 v[52:53], 12, v[40:41]
	v_lshl_add_u64 v[54:55], v[44:45], 0, v[52:53]
	s_waitcnt lgkmcnt(0)
	global_load_dwordx4 v[32:35], v[54:55], off offset:1024 nt
	global_load_dwordx4 v[36:39], v[54:55], off offset:2048 nt
	global_load_dwordx4 v[56:59], v[54:55], off offset:3072 nt
	global_load_dwordx4 v[86:89], v[54:55], off nt
	v_lshl_add_u64 v[52:53], v[46:47], 0, v[52:53]
	global_load_dwordx4 v[90:93], v[52:53], off nt
	global_load_dwordx4 v[116:119], v[52:53], off offset:1024 nt
	global_load_dwordx4 v[120:123], v[52:53], off offset:2048 nt
	global_load_dwordx4 v[124:127], v[52:53], off offset:3072 nt
	v_readlane_b32 s0, v255, 40
	v_readlane_b32 s1, v255, 41
	s_and_b64 vcc, exec, s[0:1]
	s_mov_b64 s[6:7], -1
	s_waitcnt vmcnt(7)
	v_lshlrev_b32_e32 v84, 16, v34
	s_waitcnt vmcnt(6)
	v_lshlrev_b32_e32 v74, 16, v36
	v_and_b32_e32 v75, 0xffff0000, v36
	v_lshlrev_b32_e32 v70, 16, v37
	v_and_b32_e32 v71, 0xffff0000, v37
	v_lshlrev_b32_e32 v76, 16, v38
	v_and_b32_e32 v77, 0xffff0000, v38
	v_lshlrev_b32_e32 v72, 16, v39
	v_and_b32_e32 v73, 0xffff0000, v39
	s_waitcnt vmcnt(4)
	v_lshlrev_b32_e32 v36, 16, v87
	v_and_b32_e32 v37, 0xffff0000, v87
	v_lshlrev_b32_e32 v38, 16, v86
	v_and_b32_e32 v39, 0xffff0000, v86
	v_and_b32_e32 v85, 0xffff0000, v34
	v_lshlrev_b32_e32 v80, 16, v35
	v_and_b32_e32 v81, 0xffff0000, v35
	v_lshlrev_b32_e32 v34, 16, v88
	v_and_b32_e32 v35, 0xffff0000, v88
	v_pk_mul_f32 v[106:107], v[36:37], v[36:37]
	v_pk_mul_f32 v[108:109], v[38:39], v[38:39]
	v_lshlrev_b32_e32 v82, 16, v32
	v_and_b32_e32 v83, 0xffff0000, v32
	v_lshlrev_b32_e32 v78, 16, v33
	v_and_b32_e32 v79, 0xffff0000, v33
	v_and_b32_e32 v43, 0xffff0000, v57
	v_lshlrev_b32_e32 v32, 16, v89
	v_and_b32_e32 v33, 0xffff0000, v89
	v_pk_mul_f32 v[104:105], v[34:35], v[34:35]
	v_add_f32_e32 v49, v106, v107
	v_add_f32_e32 v61, v108, v109
	v_and_b32_e32 v65, 0xffff0000, v56
	v_and_b32_e32 v51, 0xffff0000, v59
	v_mov_b32_e32 v64, v43
	v_pk_mul_f32 v[102:103], v[32:33], v[32:33]
	v_add_f32_e32 v63, v104, v105
	v_add_f32_e32 v49, v61, v49
	v_and_b32_e32 v67, 0xffff0000, v58
	v_pk_mul_f32 v[54:55], v[82:83], v[82:83]
	v_mov_b32_e32 v66, v51
	v_pk_mul_f32 v[110:111], v[64:65], v[64:65]
	v_add_f32_e32 v64, v102, v103
	v_add_f32_e32 v49, v63, v49
	v_pk_mul_f32 v[68:69], v[78:79], v[78:79]
	v_pk_mul_f32 v[112:113], v[66:67], v[66:67]
	v_add_f32_e32 v66, v54, v55
	v_add_f32_e32 v49, v64, v49
	v_pk_mul_f32 v[86:87], v[84:85], v[84:85]
	v_add_f32_e32 v102, v68, v69
	v_add_f32_e32 v49, v66, v49
	v_pk_mul_f32 v[88:89], v[80:81], v[80:81]
	v_add_f32_e32 v86, v86, v87
	v_add_f32_e32 v49, v102, v49
	v_pk_mul_f32 v[94:95], v[74:75], v[74:75]
	v_add_f32_e32 v87, v88, v89
	v_add_f32_e32 v49, v86, v49
	v_pk_mul_f32 v[96:97], v[70:71], v[70:71]
	v_add_f32_e32 v88, v94, v95
	v_add_f32_e32 v49, v87, v49
	v_pk_mul_f32 v[98:99], v[76:77], v[76:77]
	v_add_f32_e32 v89, v96, v97
	v_add_f32_e32 v49, v88, v49
	v_lshlrev_b32_e32 v60, 16, v56
	v_pk_mul_f32 v[100:101], v[72:73], v[72:73]
	v_add_f32_e32 v94, v98, v99
	v_add_f32_e32 v49, v89, v49
	v_lshlrev_b32_e32 v56, 16, v57
	v_mov_b32_e32 v57, v60
	v_add_f32_e32 v95, v100, v101
	v_add_f32_e32 v49, v94, v49
	v_lshlrev_b32_e32 v62, 16, v58
	v_pk_fma_f32 v[54:55], v[56:57], v[56:57], v[110:111]
	v_add_f32_e32 v49, v95, v49
	v_lshlrev_b32_e32 v58, 16, v59
	v_mov_b32_e32 v59, v62
	v_add_f32_e32 v49, v55, v49
	v_pk_fma_f32 v[68:69], v[58:59], v[58:59], v[112:113]
	v_add_f32_e32 v49, v54, v49
	v_add_f32_e32 v49, v69, v49
	v_add_f32_e32 v49, v68, v49
	ds_bpermute_b32 v54, v216, v49
	s_waitcnt vmcnt(3)
	v_lshlrev_b32_e32 v86, 16, v92
	v_and_b32_e32 v87, 0xffff0000, v92
	v_lshlrev_b32_e32 v88, 16, v91
	v_and_b32_e32 v89, 0xffff0000, v91
	s_waitcnt lgkmcnt(0)
	v_add_f32_e32 v49, v49, v54
	ds_bpermute_b32 v54, v217, v49
	v_lshlrev_b32_e32 v92, 16, v90
	s_waitcnt lgkmcnt(0)
	v_add_f32_e32 v49, v49, v54
	ds_bpermute_b32 v54, v218, v49
	s_waitcnt lgkmcnt(0)
	v_add_f32_e32 v49, v49, v54
	ds_bpermute_b32 v54, v219, v49
	s_waitcnt lgkmcnt(0)
	v_add_f32_e32 v55, v49, v54
	ds_bpermute_b32 v57, v220, v55
	v_lshlrev_b32_e32 v54, 16, v93
	s_waitcnt lgkmcnt(0)
	v_add_f32_e32 v57, v55, v57
	ds_bpermute_b32 v59, v221, v57
	v_and_b32_e32 v55, 0xffff0000, v93
	v_and_b32_e32 v93, 0xffff0000, v90
	s_waitcnt lgkmcnt(0)
	v_add_f32_e32 v57, v57, v59
	v_mov_b32_e32 v59, 0x358637bd
	v_fmamk_f32 v57, v57, 0x3a000000, v59
	v_mul_f32_e32 v59, 0x4b800000, v57
	v_cmp_gt_f32_e64 s[0:1], s33, v57
	s_nop 1
	v_cndmask_b32_e64 v57, v57, v59, s[0:1]
	v_rsq_f32_e32 v57, v57
	s_nop 0
	v_mul_f32_e32 v59, 0x45800000, v57
	v_cndmask_b32_e64 v68, v57, v59, s[0:1]
	v_pk_mul_f32 v[38:39], v[68:69], v[38:39] op_sel_hi:[0,1]
	v_pk_mul_f32 v[34:35], v[68:69], v[34:35] op_sel_hi:[0,1]
	v_pk_mul_f32 v[90:91], v[68:69], v[36:37] op_sel_hi:[0,1]
	v_pk_mul_f32 v[94:95], v[68:69], v[32:33] op_sel_hi:[0,1]
	v_pk_fma_f32 v[36:37], v[0:1], v[38:39], v[92:93]
	v_pk_fma_f32 v[32:33], v[4:5], v[34:35], v[86:87]
	v_pk_fma_f32 v[38:39], v[2:3], v[90:91], v[88:89]
	v_pk_fma_f32 v[34:35], v[6:7], v[94:95], v[54:55]
	s_cbranch_vccz .LBB0_755
	v_cvt_pk_bf16_f32 v86, v36, v37
	v_cvt_pk_bf16_f32 v87, v38, v39
	v_cvt_pk_bf16_f32 v88, v32, v33
	v_cvt_pk_bf16_f32 v89, v34, v35
	global_store_dwordx4 v[52:53], v[86:89], off
	v_lshlrev_b32_e32 v55, 16, v87
	v_lshlrev_b32_e32 v54, 16, v86
	v_and_b32_e32 v87, 0xffff0000, v87
	v_and_b32_e32 v86, 0xffff0000, v86
	v_pk_mul_f32 v[86:87], v[86:87], v[86:87]
	s_mov_b64 s[6:7], 0
	v_pk_fma_f32 v[54:55], v[54:55], v[54:55], v[86:87]
	v_lshlrev_b32_e32 v87, 16, v89
	v_lshlrev_b32_e32 v86, 16, v88
	v_and_b32_e32 v89, 0xffff0000, v89
	v_and_b32_e32 v88, 0xffff0000, v88
	v_pk_mul_f32 v[88:89], v[88:89], v[88:89]
	v_add_f32_e32 v49, v54, v55
	v_pk_fma_f32 v[86:87], v[86:87], v[86:87], v[88:89]
	s_nop 0
	v_add_f32_e32 v49, v49, v86
	v_add_f32_e32 v49, v49, v87
